# stick-breaking epilogue: 32 global_store_short per lane replaced by per-wave LDS transpose + 4 global_store_dwordx4 (pair narrow stores into wide ones), cvt_pk rounding
# speedup vs baseline: 1.0314x; 1.0314x over previous
; __device__ __forceinline__ bf16_t f2bf(float f) { unsigned u = __float_as_uint(f); return (bf16_t)((u + 0x7fffu + ((u >> 16) & 1u)) >> 16); }
; __device__ __forceinline__ void sb_wave(int b, int h, int qw0, int kt_lo, const bf16x8_t (&qr)[4], const bf16_t* __restrict__ K, const bf16_t* __restrict__ V, bf16_t* O, LAS unsigned char* lds, int wave, int lane) {
;     ...
;     bf16_t* Ow = O + (rowbase + qw0) * DM + h * 64;
; #pragma unroll
;     for (int r = 0; r < 16; ++r) { const int q = (r & 3) + 8 * (r >> 2) + 4 * hi; Ow[(size_t)q * DM + r32] = f2bf(o0[r]); Ow[(size_t)q * DM + 32 + r32] = f2bf(o1[r]); }
; __global__ void __launch_bounds__(MEGA_THREADS, 2) mega(MArgs a) {
;     ...
;                 for (int k = 0; k < 4; ++k) { const int bh = vcu >> 3, qb = (vcu & 7) * 4 + k; sb_unit(bh >> 4, bh & 15, qb * 256, SQ, SK, SV, H, lds, tid); }
.LBB9_555:
	s_ashr_i32 s67, s66, 31
	s_lshl_b64 s[8:9], s[66:67], 11
	s_nop 3
	v_readfirstlane_b32 s5, v228
	s_ashr_i32 s5, s5, 6
	s_lshl_b32 s5, s5, 12
	s_add_i32 s5, s5, 0x1ba00
	v_and_b32_e32 v0, 31, v244
	v_lshrrev_b32_e32 v34, 5, v244
	v_lshlrev_b32_e32 v0, 1, v0
	v_lshl_add_u32 v34, v34, 9, v0
	v_add_u32_e32 v34, s5, v34
	v_lshl_add_u32 v35, v244, 4, s5
	v_cvt_pk_bf16_f32 v2, v2, v2
	ds_write_b16 v34, v2 offset:0
	v_cvt_pk_bf16_f32 v18, v18, v18
	ds_write_b16 v34, v18 offset:64
	v_cvt_pk_bf16_f32 v3, v3, v3
	ds_write_b16 v34, v3 offset:128
	v_cvt_pk_bf16_f32 v19, v19, v19
	ds_write_b16 v34, v19 offset:192
	v_cvt_pk_bf16_f32 v4, v4, v4
	ds_write_b16 v34, v4 offset:256
	v_cvt_pk_bf16_f32 v20, v20, v20
	ds_write_b16 v34, v20 offset:320
	v_cvt_pk_bf16_f32 v5, v5, v5
	ds_write_b16 v34, v5 offset:384
	v_cvt_pk_bf16_f32 v21, v21, v21
	ds_write_b16 v34, v21 offset:448
	v_cvt_pk_bf16_f32 v6, v6, v6
	ds_write_b16 v34, v6 offset:1024
	v_cvt_pk_bf16_f32 v22, v22, v22
	ds_write_b16 v34, v22 offset:1088
	v_cvt_pk_bf16_f32 v7, v7, v7
	ds_write_b16 v34, v7 offset:1152
	v_cvt_pk_bf16_f32 v23, v23, v23
	ds_write_b16 v34, v23 offset:1216
	v_cvt_pk_bf16_f32 v8, v8, v8
	ds_write_b16 v34, v8 offset:1280
	v_cvt_pk_bf16_f32 v24, v24, v24
	ds_write_b16 v34, v24 offset:1344
	v_cvt_pk_bf16_f32 v9, v9, v9
	ds_write_b16 v34, v9 offset:1408
	v_cvt_pk_bf16_f32 v25, v25, v25
	ds_write_b16 v34, v25 offset:1472
	v_cvt_pk_bf16_f32 v10, v10, v10
	ds_write_b16 v34, v10 offset:2048
	v_cvt_pk_bf16_f32 v26, v26, v26
	ds_write_b16 v34, v26 offset:2112
	v_cvt_pk_bf16_f32 v11, v11, v11
	ds_write_b16 v34, v11 offset:2176
	v_cvt_pk_bf16_f32 v27, v27, v27
	ds_write_b16 v34, v27 offset:2240
	v_cvt_pk_bf16_f32 v12, v12, v12
	ds_write_b16 v34, v12 offset:2304
	v_cvt_pk_bf16_f32 v28, v28, v28
	ds_write_b16 v34, v28 offset:2368
	v_cvt_pk_bf16_f32 v13, v13, v13
	ds_write_b16 v34, v13 offset:2432
	v_cvt_pk_bf16_f32 v29, v29, v29
	ds_write_b16 v34, v29 offset:2496
	v_cvt_pk_bf16_f32 v14, v14, v14
	ds_write_b16 v34, v14 offset:3072
	v_cvt_pk_bf16_f32 v30, v30, v30
	ds_write_b16 v34, v30 offset:3136
	v_cvt_pk_bf16_f32 v15, v15, v15
	ds_write_b16 v34, v15 offset:3200
	v_cvt_pk_bf16_f32 v31, v31, v31
	ds_write_b16 v34, v31 offset:3264
	v_cvt_pk_bf16_f32 v16, v16, v16
	ds_write_b16 v34, v16 offset:3328
	v_cvt_pk_bf16_f32 v32, v32, v32
	ds_write_b16 v34, v32 offset:3392
	v_cvt_pk_bf16_f32 v17, v17, v17
	ds_write_b16 v34, v17 offset:3456
	v_cvt_pk_bf16_f32 v33, v33, v33
	ds_write_b16 v34, v33 offset:3520
	s_waitcnt lgkmcnt(0)
	ds_read_b128 v[2:5], v35
	ds_read_b128 v[6:9], v35 offset:1024
	ds_read_b128 v[10:13], v35 offset:2048
	ds_read_b128 v[14:17], v35 offset:3072
	v_and_b32_e32 v0, 31, v244
	v_lshrrev_b32_e32 v18, 5, v244
	v_lshlrev_b32_e32 v0, 1, v0
	v_lshl_add_u32 v0, v18, 13, v0
	v_lshrrev_b32_e32 v18, 3, v244
	v_and_b32_e32 v19, 7, v244
	v_lshlrev_b32_e32 v19, 4, v19
	v_lshl_add_u32 v18, v18, 11, v19
	v_sub_u32_e32 v0, v18, v0
	v_lshl_add_u64 v[34:35], v[84:85], 0, s[8:9]
	v_lshl_add_u64 v[34:35], v[34:35], 0, v[0:1]
	s_mov_b64 s[8:9], 0x4000
	v_lshl_add_u64 v[18:19], v[34:35], 0, s[8:9]
	v_lshl_add_u64 v[20:21], v[18:19], 0, s[8:9]
	v_lshl_add_u64 v[22:23], v[20:21], 0, s[8:9]
	s_waitcnt lgkmcnt(0)
	global_store_dwordx4 v[34:35], v[2:5], off
	global_store_dwordx4 v[18:19], v[6:9], off
	global_store_dwordx4 v[20:21], v[10:13], off
	global_store_dwordx4 v[22:23], v[14:17], off
	s_add_i32 s4, s4, 1
	s_add_i32 s3, s3, 8
	s_cmp_lg_u32 s4, 4
	s_barrier
	s_cbranch_scc0 .LBB9_580
